# v29 + SB: K-fragment reads hoisted at unit start too, next-tile prefetch issue moved into the S-MFMA dependency shadow (replaces s_nop 11)
# baseline (speedup 1.0000x reference)
; __device__ __forceinline__ void sb_mfma(const bf16_t* __restrict__ proj, bf16_t* __restrict__ mix, LAS unsigned char* ldsl) {
;     ...
;         const int g = unit & 127, h = (unit >> 7) & 15, b = unit >> 11;
;         const size_t rowb = (size_t)b * SEQ;
;         const int t0 = g * 32;
;         const bf16_t* hb = proj + rowb * 3072 + h * 64;
;         u32x4 kt[4], vt4[4], qf[4];
;         tile_load_nt(qf, hb + (size_t)t0 * 3072, 3072, lane);
;         tile_load(kt, hb + (size_t)t0 * 3072 + 1024, 3072, lane);
;         tile_load(vt4, hb + (size_t)t0 * 3072 + 2048, 3072, lane);
;         tile_to_lds(kimg, qf, lane);
;         frag_read(qf, kimg, r32, hi);
;         f32x16 o0, o1;
; #pragma unroll
;         for (int r = 0; r < 16; ++r) { o0[r] = 0.f; o1[r] = 0.f; }
;         float A = 1.f;
;         for (int kb = t0; kb >= 0; kb -= 32) {
;             tile_to_lds(kimg, kt, lane);
;             tile_to_lds(vimg, vt4, lane);
;             if (kb >= 32) {
;                 tile_load(kt, hb + (size_t)(kb - 32) * 3072 + 1024, 3072, lane);
;                 tile_load(vt4, hb + (size_t)(kb - 32) * 3072 + 2048, 3072, lane);
;             }
;             u32x4 kf[4];
;             frag_read(kf, kimg, r32, hi);
;             f32x16 s;
; #pragma unroll
;             for (int r = 0; r < 16; ++r) s[r] = 0.f;
; #pragma unroll
;             for (int d0 = 0; d0 < 4; ++d0) s = __builtin_amdgcn_mfma_f32_32x32x16_bf16(as_bf(kf[d0]), as_bf(qf[d0]), s, 0, 0, 0);
.LBB0_272:
	s_ashr_i32 s40, s44, 11
	s_lshl_b32 s41, s44, 5
	s_and_b32 s45, s41, 0xfe0
	s_mul_i32 s46, s40, 0x1800000
	s_mul_hi_i32 s41, s40, 0x1800000
	s_add_u32 s47, s98, s46
	s_addc_u32 s48, s99, s41
	s_lshr_b32 s41, s44, 1
	s_and_b32 s41, s41, 0x3c0
	s_lshl_b32 s46, s41, 1
	s_add_u32 s41, s47, s46
	s_addc_u32 s47, s48, 0
	s_mul_i32 s48, s45, 0x1800
	s_add_u32 s48, s41, s48
	s_addc_u32 s49, s47, 0
	v_lshlrev_b32_e32 v148, 1, v96
	v_lshl_add_u64 v[0:1], s[48:49], 0, v[148:149]
	v_lshlrev_b32_e32 v104, 1, v98
	v_mov_b32_e32 v105, v149
	v_lshl_add_u64 v[16:17], v[0:1], 0, v[104:105]
	v_add_co_u32_e32 v18, vcc, s56, v16
	s_mov_b32 s48, 0xd000
	s_nop 0
	v_addc_co_u32_e32 v19, vcc, 0, v17, vcc
	v_add_co_u32_e32 v20, vcc, s48, v16
	s_mov_b32 s48, 0x19000
	s_nop 0
	v_addc_co_u32_e32 v21, vcc, 0, v17, vcc
	v_add_co_u32_e32 v22, vcc, s60, v16
	global_load_dwordx4 v[0:3], v[16:17], off nt
	global_load_dwordx4 v[4:7], v[20:21], off offset:-4096 nt
	v_addc_co_u32_e32 v23, vcc, 0, v17, vcc
	v_add_co_u32_e32 v24, vcc, s48, v16
	s_mov_b32 s48, 0x25000
	s_nop 0
	v_addc_co_u32_e32 v25, vcc, 0, v17, vcc
	v_add_co_u32_e32 v26, vcc, s33, v16
	global_load_dwordx4 v[8:11], v[24:25], off offset:-4096 nt
	s_nop 0
	v_addc_co_u32_e32 v27, vcc, 0, v17, vcc
	v_add_co_u32_e32 v28, vcc, s48, v16
	s_movk_i32 s48, 0x1000
	s_nop 0
	v_addc_co_u32_e32 v29, vcc, 0, v17, vcc
	global_load_dwordx4 v[12:15], v[28:29], off offset:-4096 nt
	global_load_dwordx4 v[64:67], v[16:17], off offset:2048
	global_load_dwordx4 v[68:71], v[18:19], off offset:2048
	global_load_dwordx4 v[72:75], v[22:23], off offset:2048
	v_add_co_u32_e32 v16, vcc, s48, v16
	s_cmp_eq_u32 s45, 0
	s_nop 0
	v_addc_co_u32_e32 v17, vcc, 0, v17, vcc
	global_load_dwordx4 v[76:79], v[26:27], off offset:2048
	global_load_dwordx4 v[80:83], v[16:17], off
	global_load_dwordx4 v[84:87], v[20:21], off
	global_load_dwordx4 v[88:91], v[24:25], off
	global_load_dwordx4 v[92:95], v[28:29], off
	s_waitcnt vmcnt(11)
	ds_write_b128 v106, v[0:3]
	s_waitcnt vmcnt(10)
	ds_write_b128 v106, v[4:7] offset:1152
	s_waitcnt vmcnt(9)
	ds_write_b128 v106, v[8:11] offset:2304
	s_waitcnt vmcnt(8)
	ds_write_b128 v106, v[12:15] offset:3456
	ds_read_b128 v[48:51], v107
	ds_read_b128 v[52:55], v107 offset:32
	ds_read_b128 v[56:59], v107 offset:64
	ds_read_b128 v[60:63], v107 offset:96
	s_waitcnt vmcnt(7)
	ds_write_b128 v106, v[64:67]
	s_waitcnt vmcnt(6)
	ds_write_b128 v106, v[68:71] offset:1152
	s_waitcnt vmcnt(5)
	ds_write_b128 v106, v[72:75] offset:2304
	s_waitcnt vmcnt(4)
	ds_write_b128 v106, v[76:79] offset:3456
	ds_read_b128 v[118:121], v107
	ds_read_b128 v[110:113], v107 offset:32
	ds_read_b128 v[122:125], v107 offset:64
	ds_read_b128 v[114:117], v107 offset:96
	s_waitcnt vmcnt(3)
	ds_write_b128 v106, v[80:83] offset:4608
	s_waitcnt vmcnt(2)
	ds_write_b128 v106, v[84:87] offset:5760
	s_waitcnt vmcnt(1)
	ds_write_b128 v106, v[88:91] offset:6912
	s_waitcnt vmcnt(0)
	ds_write_b128 v106, v[92:95] offset:8064
	s_cbranch_scc1 .LBB0_274
	s_sub_i32 s48, s45, 32
	s_mul_hi_u32 s49, s48, 0x1800
	s_mulk_i32 s48, 0x1800
	s_add_u32 s48, s41, s48
	s_addc_u32 s49, s47, s49
	v_lshl_add_u64 v[0:1], s[48:49], 0, v[148:149]
	v_lshl_add_u64 v[0:1], v[0:1], 0, v[104:105]
	v_add_co_u32_e32 v2, vcc, s56, v0
	s_nop 1
	v_addc_co_u32_e32 v3, vcc, 0, v1, vcc
	global_load_dwordx4 v[64:67], v[0:1], off offset:2048
	global_load_dwordx4 v[68:71], v[2:3], off offset:2048
	v_add_co_u32_e32 v2, vcc, s60, v0
	s_nop 1
	v_addc_co_u32_e32 v3, vcc, 0, v1, vcc
	v_add_co_u32_e32 v4, vcc, s33, v0
	s_nop 1
	v_addc_co_u32_e32 v5, vcc, 0, v1, vcc
	global_load_dwordx4 v[72:75], v[2:3], off offset:2048
	global_load_dwordx4 v[76:79], v[4:5], off offset:2048
	v_add_co_u32_e32 v2, vcc, 0x1000, v0
	s_nop 1
	v_addc_co_u32_e32 v3, vcc, 0, v1, vcc
	v_add_co_u32_e32 v4, vcc, 0xd000, v0
	s_nop 1
	v_addc_co_u32_e32 v5, vcc, 0, v1, vcc
	global_load_dwordx4 v[80:83], v[2:3], off
	global_load_dwordx4 v[84:87], v[4:5], off
	v_add_co_u32_e32 v2, vcc, 0x19000, v0
	s_nop 1
	v_addc_co_u32_e32 v3, vcc, 0, v1, vcc
	v_add_co_u32_e32 v0, vcc, 0x25000, v0
	s_nop 1
	v_addc_co_u32_e32 v1, vcc, 0, v1, vcc
	global_load_dwordx4 v[88:91], v[2:3], off
	global_load_dwordx4 v[92:95], v[0:1], off
.LBB0_274:
	s_waitcnt lgkmcnt(7)
	v_mfma_f32_32x32x16_bf16 v[0:15], v[118:121], v[48:51], 0
	s_waitcnt lgkmcnt(6)
	v_mfma_f32_32x32x16_bf16 v[0:15], v[110:113], v[52:55], v[0:15]
	s_waitcnt lgkmcnt(5)
	v_mfma_f32_32x32x16_bf16 v[0:15], v[122:125], v[56:59], v[0:15]
	s_waitcnt lgkmcnt(4)
; __device__ __forceinline__ unsigned pk2(float lo, float hi) { return pg8::cvt_pk_bf16(lo, hi); }
; __device__ __forceinline__ int crow(int r, int hi) { return (r & 3) + 8 * (r >> 2) + 4 * hi; }
; __device__ __forceinline__ void sb_mfma(const bf16_t* __restrict__ proj, bf16_t* __restrict__ mix, LAS unsigned char* ldsl) {
;     ...
;             for (int d0 = 0; d0 < 4; ++d0) s = __builtin_amdgcn_mfma_f32_32x32x16_bf16(as_bf(kf[d0]), as_bf(qf[d0]), s, 0, 0, 0);
;             const bool diag = (kb == t0);
;             float bt[16], kp1[16];
; #pragma unroll
;             for (int r = 0; r < 16; ++r) {
;                 const float z = fmaxf(s[r], -126.f);
;                 const float a = __builtin_amdgcn_exp2f(-z), rc = __builtin_amdgcn_rcpf(1.f + a);
;                 float be = rc, ke = a * rc;
;                 if (diag) { const bool valid = crow(r, hi) < r32; be = valid ? be : 0.f; ke = valid ? ke : 1.f; }
;                 bt[r] = be; kp1[r] = ke;
;             }
;             float gs[4], X[4];
; #pragma unroll
;             for (int c = 0; c < 4; ++c) { const float g4 = (kp1[4 * c] * kp1[4 * c + 1]) * (kp1[4 * c + 2] * kp1[4 * c + 3]); const HalfPair hp = half_swap(g4);
;                 gs[c] = hp.a * hp.b; X[c] = hi == 0 ? hp.b : 1.f; }
;             const float S2 = gs[3], S1 = S2 * gs[2], S0 = S1 * gs[1], total = S0 * gs[0];
;             const float SS[4] = {S0, S1, S2, 1.f};
;             float w[16];
; #pragma unroll
;             for (int c = 0; c < 4; ++c) {
;                 float run = A * SS[c] * X[c];
;                 w[4 * c + 3] = bt[4 * c + 3] * run; run *= kp1[4 * c + 3];
;                 w[4 * c + 2] = bt[4 * c + 2] * run; run *= kp1[4 * c + 2];
;                 w[4 * c + 1] = bt[4 * c + 1] * run; run *= kp1[4 * c + 1];
;                 w[4 * c + 0] = bt[4 * c + 0] * run;
;             }
;             A *= total;
;             u32x4 pb[2];
; #pragma unroll
;             for (int kk = 0; kk < 2; ++kk) { pb[kk].x = pk2(w[8 * kk], w[8 * kk + 1]); pb[kk].y = pk2(w[8 * kk + 2], w[8 * kk + 3]);
;                 pb[kk].z = pk2(w[8 * kk + 4], w[8 * kk + 5]); pb[kk].w = pk2(w[8 * kk + 6], w[8 * kk + 7]); }
;             pv_tile_tr(vimg, pb, o0, o1, r32, hi);
;             if (__all(A < 1.17549435e-38f)) break;
	v_mfma_f32_32x32x16_bf16 v[0:15], v[114:117], v[60:63], v[0:15]
	s_nop 11
	v_max_f32_e64 v6, -v6, -v6
	v_min_f32_e32 v6, 0x42fc0000, v6
	v_exp_f32_e32 v6, v6
	v_max_f32_e64 v0, -v0, -v0
	v_min_f32_e32 v0, 0x42fc0000, v0
	v_exp_f32_e32 v0, v0
	v_add_f32_e32 v22, 1.0, v6
	v_rcp_f32_e32 v22, v22
	v_max_f32_e64 v1, -v1, -v1
	v_add_f32_e32 v16, 1.0, v0
	v_min_f32_e32 v1, 0x42fc0000, v1
	v_mul_f32_e32 v6, v6, v22
	v_cndmask_b32_e64 v23, 1.0, v6, s[16:17]
	v_max_f32_e64 v6, -v7, -v7
	v_min_f32_e32 v6, 0x42fc0000, v6
	v_exp_f32_e32 v6, v6
	v_rcp_f32_e32 v16, v16
	v_exp_f32_e32 v1, v1
	v_max_f32_e64 v2, -v2, -v2
	v_add_f32_e32 v7, 1.0, v6
	v_rcp_f32_e32 v7, v7
	v_mul_f32_e32 v17, v0, v16
	v_cndmask_b32_e64 v0, 0, v16, s[4:5]
	v_add_f32_e32 v16, 1.0, v1
	v_mul_f32_e32 v6, v6, v7
	v_cndmask_b32_e64 v25, 1.0, v6, s[18:19]
	v_max_f32_e64 v6, -v8, -v8
	v_min_f32_e32 v6, 0x42fc0000, v6
	v_exp_f32_e32 v6, v6
	v_cndmask_b32_e64 v24, 0, v7, s[18:19]
	v_rcp_f32_e32 v16, v16
	v_min_f32_e32 v2, 0x42fc0000, v2
	v_add_f32_e32 v7, 1.0, v6
	v_rcp_f32_e32 v7, v7
	v_exp_f32_e32 v2, v2
	v_mul_f32_e32 v18, v1, v16
	v_cndmask_b32_e64 v1, 0, v16, s[6:7]
	v_mul_f32_e32 v6, v6, v7
	v_cndmask_b32_e64 v27, 1.0, v6, s[20:21]
	v_max_f32_e64 v6, -v9, -v9
	v_min_f32_e32 v6, 0x42fc0000, v6
	v_exp_f32_e32 v6, v6
	v_cndmask_b32_e64 v26, 0, v7, s[20:21]
	v_cndmask_b32_e64 v16, 1.0, v18, s[6:7]
	v_add_f32_e32 v18, 1.0, v2
	v_add_f32_e32 v7, 1.0, v6
	v_rcp_f32_e32 v7, v7
	v_max_f32_e64 v3, -v3, -v3
	v_rcp_f32_e32 v18, v18
	v_min_f32_e32 v3, 0x42fc0000, v3
	v_mul_f32_e32 v6, v6, v7
	v_cndmask_b32_e64 v29, 1.0, v6, s[22:23]
	v_max_f32_e64 v6, -v10, -v10
	v_min_f32_e32 v6, 0x42fc0000, v6
	v_exp_f32_e32 v6, v6
	v_cndmask_b32_e64 v28, 0, v7, s[22:23]
	v_exp_f32_e32 v3, v3
	v_mul_f32_e32 v19, v2, v18
	v_add_f32_e32 v7, 1.0, v6
	v_rcp_f32_e32 v7, v7
	v_cndmask_b32_e64 v2, 0, v18, s[8:9]
	v_cndmask_b32_e64 v18, 1.0, v19, s[8:9]
	v_add_f32_e32 v19, 1.0, v3
	v_mul_f32_e32 v6, v6, v7
	v_cndmask_b32_e64 v31, 1.0, v6, s[24:25]
	v_max_f32_e64 v6, -v11, -v11
	v_min_f32_e32 v6, 0x42fc0000, v6
	v_exp_f32_e32 v6, v6
	v_cndmask_b32_e64 v30, 0, v7, s[24:25]
	v_max_f32_e64 v4, -v4, -v4
	v_rcp_f32_e32 v19, v19
	v_add_f32_e32 v7, 1.0, v6
	v_rcp_f32_e32 v7, v7
	v_min_f32_e32 v4, 0x42fc0000, v4
	v_exp_f32_e32 v4, v4
	v_mul_f32_e32 v20, v3, v19
	v_mul_f32_e32 v6, v6, v7
	v_cndmask_b32_e64 v33, 1.0, v6, s[26:27]
	v_max_f32_e64 v6, -v12, -v12
	v_min_f32_e32 v6, 0x42fc0000, v6
	v_exp_f32_e32 v6, v6
	v_cndmask_b32_e64 v32, 0, v7, s[26:27]
	v_cndmask_b32_e64 v3, 0, v19, s[10:11]
	v_cndmask_b32_e64 v19, 1.0, v20, s[10:11]
	v_add_f32_e32 v7, 1.0, v6
	v_rcp_f32_e32 v7, v7
	v_add_f32_e32 v20, 1.0, v4
	v_max_f32_e64 v5, -v5, -v5
	v_rcp_f32_e32 v20, v20
	v_mul_f32_e32 v6, v6, v7
	v_cndmask_b32_e64 v9, 1.0, v6, s[28:29]
	v_max_f32_e64 v6, -v13, -v13
	v_min_f32_e32 v6, 0x42fc0000, v6
	v_exp_f32_e32 v6, v6
	v_cndmask_b32_e64 v34, 0, v7, s[28:29]
	v_min_f32_e32 v5, 0x42fc0000, v5
	v_exp_f32_e32 v5, v5
	v_add_f32_e32 v7, 1.0, v6
	v_rcp_f32_e32 v7, v7
	v_mul_f32_e32 v21, v4, v20
	v_cndmask_b32_e64 v4, 0, v20, s[12:13]
	v_cndmask_b32_e64 v20, 1.0, v21, s[12:13]
	v_mul_f32_e32 v6, v6, v7
	v_cndmask_b32_e64 v36, 1.0, v6, s[30:31]
	v_max_f32_e64 v6, -v14, -v14
	v_min_f32_e32 v6, 0x42fc0000, v6
	v_exp_f32_e32 v6, v6
	v_cndmask_b32_e64 v35, 0, v7, s[30:31]
	v_add_f32_e32 v21, 1.0, v5
	v_rcp_f32_e32 v21, v21
	v_add_f32_e32 v7, 1.0, v6
	v_rcp_f32_e32 v7, v7
	v_cndmask_b32_e64 v17, 1.0, v17, s[4:5]
	v_mul_f32_e32 v5, v5, v21
	v_cndmask_b32_e64 v5, 1.0, v5, s[14:15]
	v_mul_f32_e32 v6, v6, v7
	v_cndmask_b32_e64 v37, 1.0, v6, s[34:35]
	v_max_f32_e64 v6, -v15, -v15
	v_min_f32_e32 v6, 0x42fc0000, v6
	v_exp_f32_e32 v6, v6
	v_cndmask_b32_e64 v14, 0, v7, s[34:35]
	v_mul_f32_e32 v10, v23, v25
	v_mul_f32_e32 v11, v31, v33
	v_add_f32_e32 v7, 1.0, v6
	v_rcp_f32_e32 v7, v7
	v_mul_f32_e32 v9, v9, v36
	v_cndmask_b32_e64 v22, 0, v22, s[16:17]
	v_cndmask_b32_e64 v21, 0, v21, s[14:15]
	v_mul_f32_e32 v6, v6, v7
	v_cndmask_b32_e64 v15, 1.0, v6, s[36:37]
	v_cndmask_b32_e64 v38, 0, v7, s[36:37]
	v_mul_f32_e32 v6, v17, v16
	v_mul_f32_e32 v7, v18, v19
	v_mul_f32_e32 v6, v6, v7
	v_mul_f32_e32 v7, v20, v5
	v_mul_f32_e32 v7, v7, v10
	v_mov_b32_e32 v10, v7
	s_nop 1
	v_permlane32_swap_b32_e32 v7, v10
	v_mul_f32_e32 v7, v7, v10
	v_cndmask_b32_e64 v20, 1.0, v10, s[0:1]
	v_mul_f32_e32 v10, v27, v29
	v_mul_f32_e32 v10, v10, v11
	v_mul_f32_e32 v11, v37, v15
	v_mul_f32_e32 v11, v9, v11
	v_mov_b32_e32 v12, v10
	v_mov_b32_e32 v13, v11
	s_nop 0
	v_permlane32_swap_b32_e32 v10, v12
	v_permlane32_swap_b32_e32 v11, v13
	v_pk_mul_f32 v[10:11], v[10:11], v[12:13]
	v_mov_b32_e32 v8, v6
	v_cndmask_b32_e64 v27, 1.0, v12, s[0:1]
	v_cndmask_b32_e64 v39, 1.0, v13, s[0:1]
	v_pk_mul_f32 v[12:13], v[10:11], v[10:11] op_sel:[0,1] op_sel_hi:[1,0]
	v_permlane32_swap_b32_e32 v6, v8
	v_mov_b32_e32 v9, v12
	v_cndmask_b32_e64 v17, 1.0, v8, s[0:1]
	v_pk_mul_f32 v[6:7], v[6:7], v[8:9]
	v_mul_f32_e32 v15, v39, v15
	v_mul_f32_e32 v8, v17, v7
	v_mul_f32_e32 v3, v3, v8
	v_mul_f32_e32 v8, v19, v8
	v_mul_f32_e32 v2, v2, v8
	v_mul_f32_e32 v8, v18, v8
	v_mul_f32_e32 v1, v1, v8
	v_mul_f32_e32 v8, v16, v8
	v_mul_f32_e32 v0, v0, v8
	v_mul_f32_e32 v8, v20, v12
	v_mul_f32_e32 v9, v24, v8
	v_mul_f32_e32 v8, v25, v8
	v_mul_f32_e32 v10, v22, v8
	v_mul_f32_e32 v8, v23, v8
	v_mul_f32_e32 v5, v5, v8
	v_mul_f32_e32 v4, v4, v5
	v_mul_f32_e32 v5, v27, v11
	v_mul_f32_e32 v12, v21, v8
	v_mul_f32_e32 v8, v32, v5
	v_mul_f32_e32 v5, v33, v5
	v_mul_f32_e32 v11, v30, v5
	v_mul_f32_e32 v5, v31, v5
	v_mul_f32_e32 v13, v28, v5
	v_mul_f32_e32 v5, v29, v5
	v_mul_f32_e32 v14, v14, v15
	v_mul_f32_e32 v15, v37, v15
	v_mul_f32_e32 v5, v26, v5
	v_mul_f32_e32 v17, v35, v15
	v_mul_f32_e32 v15, v36, v15
	v_mul_f32_e32 v16, v38, v39
	v_mul_f32_e32 v15, v34, v15
	v_mul_f32_e32 v101, v6, v7
	v_cvt_pk_bf16_f32 v0, v0, v1
	v_cvt_pk_bf16_f32 v1, v2, v3
	v_cvt_pk_bf16_f32 v2, v4, v12
	v_cvt_pk_bf16_f32 v3, v10, v9
	v_cvt_pk_bf16_f32 v32, v5, v13
	v_cvt_pk_bf16_f32 v33, v11, v8
	v_cvt_pk_bf16_f32 v34, v15, v17
	v_cvt_pk_bf16_f32 v35, v14, v16
	ds_read_b64_tr_b16 v[4:5], v108 offset:4608
	ds_read_b64_tr_b16 v[6:7], v108 offset:5760
	ds_read_b64_tr_b16 v[8:9], v108 offset:4672
	ds_read_b64_tr_b16 v[10:11], v108 offset:5824
	s_waitcnt lgkmcnt(2)
	v_mfma_f32_32x32x16_bf16 v[16:31], v[4:7], v[0:3], 0
	ds_read_b64_tr_b16 v[36:37], v108 offset:6912
	ds_read_b64_tr_b16 v[38:39], v108 offset:8064
	ds_read_b64_tr_b16 v[40:41], v108 offset:6976
	ds_read_b64_tr_b16 v[42:43], v108 offset:8128
	v_cmp_gt_f32_e32 vcc, s3, v101
	s_cmp_eq_u64 vcc, exec
	s_cselect_b64 s[48:49], -1, 0
	s_cmp_eq_u32 s45, 0
	s_cselect_b64 s[50:51], -1, 0
	s_or_b64 s[48:49], s[50:51], s[48:49]
	s_waitcnt lgkmcnt(4)
	v_mfma_f32_32x32x16_bf16 v[0:15], v[8:11], v[0:3], 0
	s_and_b64 vcc, exec, s[48:49]
	s_mov_b32 s48, s45
	s_waitcnt lgkmcnt(2)
	v_mfma_f32_32x32x16_bf16 v[16:31], v[36:39], v[32:35], v[16:31]
	s_waitcnt lgkmcnt(0)
	v_mfma_f32_32x32x16_bf16 v[0:15], v[40:43], v[32:35], v[0:15]
	s_cbranch_vccz .LBB0_276
	s_branch .LBB0_271
; __device__ __forceinline__ void sb_mfma(const bf16_t* __restrict__ proj, bf16_t* __restrict__ mix, LAS unsigned char* ldsl) {
;     ...
;             if (kb >= 32) {
;                 tile_load(kt, hb + (size_t)(kb - 32) * 3072 + 1024, 3072, lane);
;                 tile_load(vt4, hb + (size_t)(kb - 32) * 3072 + 2048, 3072, lane);
;             }
;             u32x4 kf[4];
;             frag_read(kf, kimg, r32, hi);
;             f32x16 s;
; #pragma unroll
;             for (int r = 0; r < 16; ++r) s[r] = 0.f;
; #pragma unroll
;             for (int d0 = 0; d0 < 4; ++d0) s = __builtin_amdgcn_mfma_f32_32x32x16_bf16(as_bf(kf[d0]), as_bf(qf[d0]), s, 0, 0, 0);
.LBB0_275:
	s_waitcnt lgkmcnt(7)
	v_mfma_f32_32x32x16_bf16 v[32:47], v[118:121], v[48:51], 0
	s_waitcnt lgkmcnt(6)
	v_mfma_f32_32x32x16_bf16 v[32:47], v[110:113], v[52:55], v[32:47]
	s_waitcnt lgkmcnt(5)
	v_mfma_f32_32x32x16_bf16 v[32:47], v[122:125], v[56:59], v[32:47]
	s_waitcnt lgkmcnt(4)
	v_mfma_f32_32x32x16_bf16 v[32:47], v[114:117], v[60:63], v[32:47]
	s_cbranch_scc1 .Lsb_nopf
	s_sub_i32 s49, s48, 64
	s_mul_hi_u32 s51, s49, 0x1800
	s_mulk_i32 s49, 0x1800
	s_add_u32 s50, s41, s49
	s_addc_u32 s51, s47, s51
	v_lshl_add_u64 v[126:127], s[50:51], 0, v[148:149]
	v_mov_b32_e32 v105, v149
	v_lshl_add_u64 v[126:127], v[126:127], 0, v[104:105]
	v_add_co_u32_e32 v128, vcc, s56, v126
	s_nop 1
	v_addc_co_u32_e32 v129, vcc, 0, v127, vcc
	global_load_dwordx4 v[64:67], v[126:127], off offset:2048
	global_load_dwordx4 v[68:71], v[128:129], off offset:2048
	v_add_co_u32_e32 v128, vcc, s60, v126
	s_nop 1
	v_addc_co_u32_e32 v129, vcc, 0, v127, vcc
	v_add_co_u32_e32 v130, vcc, s33, v126
	s_nop 1
	v_addc_co_u32_e32 v131, vcc, 0, v127, vcc
	global_load_dwordx4 v[72:75], v[128:129], off offset:2048
	global_load_dwordx4 v[76:79], v[130:131], off offset:2048
	v_add_co_u32_e32 v128, vcc, 0x1000, v126
	s_nop 1
	v_addc_co_u32_e32 v129, vcc, 0, v127, vcc
	v_add_co_u32_e32 v130, vcc, 0xd000, v126
	s_nop 1
	v_addc_co_u32_e32 v131, vcc, 0, v127, vcc
	global_load_dwordx4 v[80:83], v[128:129], off
	global_load_dwordx4 v[84:87], v[130:131], off
	v_add_co_u32_e32 v128, vcc, 0x19000, v126
	s_nop 1
	v_addc_co_u32_e32 v129, vcc, 0, v127, vcc
	v_add_co_u32_e32 v126, vcc, 0x25000, v126
	s_nop 1
	v_addc_co_u32_e32 v127, vcc, 0, v127, vcc
	global_load_dwordx4 v[88:91], v[128:129], off
	global_load_dwordx4 v[92:95], v[126:127], off
	s_branch .Lsb_pfd
.Lsb_nopf:
	s_nop 11
; __device__ __forceinline__ void sb_mfma(const bf16_t* __restrict__ proj, bf16_t* __restrict__ mix, LAS unsigned char* ldsl) {
;     ...
;             tile_to_lds(kimg, kt, lane);
;             tile_to_lds(vimg, vt4, lane);
;             if (kb >= 32) {
;                 tile_load(kt, hb + (size_t)(kb - 32) * 3072 + 1024, 3072, lane);
;                 tile_load(vt4, hb + (size_t)(kb - 32) * 3072 + 2048, 3072, lane);
;             }
;             u32x4 kf[4];
;             frag_read(kf, kimg, r32, hi);
;             f32x16 s;
; #pragma unroll
;             for (int r = 0; r < 16; ++r) s[r] = 0.f;
; #pragma unroll
;             for (int d0 = 0; d0 < 4; ++d0) s = __builtin_amdgcn_mfma_f32_32x32x16_bf16(as_bf(kf[d0]), as_bf(qf[d0]), s, 0, 0, 0);
;             const bool diag = (kb == t0);
;             float bt[16], kp1[16];
; #pragma unroll
;             for (int r = 0; r < 16; ++r) {
;                 const float z = fmaxf(s[r], -126.f);
;                 const float a = __builtin_amdgcn_exp2f(-z), rc = __builtin_amdgcn_rcpf(1.f + a);
;                 float be = rc, ke = a * rc;
;                 if (diag) { const bool valid = crow(r, hi) < r32; be = valid ? be : 0.f; ke = valid ? ke : 1.f; }
;                 bt[r] = be; kp1[r] = ke;
;             }
;             float gs[4], X[4];
; #pragma unroll
;             for (int c = 0; c < 4; ++c) { const float g4 = (kp1[4 * c] * kp1[4 * c + 1]) * (kp1[4 * c + 2] * kp1[4 * c + 3]); const HalfPair hp = half_swap(g4);
;                 gs[c] = hp.a * hp.b; X[c] = hi == 0 ? hp.b : 1.f; }
;             const float S2 = gs[3], S1 = S2 * gs[2], S0 = S1 * gs[1], total = S0 * gs[0];
;             const float SS[4] = {S0, S1, S2, 1.f};
;             float w[16];
; #pragma unroll
;             for (int c = 0; c < 4; ++c) {
;                 float run = A * SS[c] * X[c];
;                 w[4 * c + 3] = bt[4 * c + 3] * run; run *= kp1[4 * c + 3];
;                 w[4 * c + 2] = bt[4 * c + 2] * run; run *= kp1[4 * c + 2];
;                 w[4 * c + 1] = bt[4 * c + 1] * run; run *= kp1[4 * c + 1];
;                 w[4 * c + 0] = bt[4 * c + 0] * run;
;             }
;             A *= total;
;             u32x4 pb[2];
; #pragma unroll
;             for (int kk = 0; kk < 2; ++kk) { pb[kk].x = pk2(w[8 * kk], w[8 * kk + 1]); pb[kk].y = pk2(w[8 * kk + 2], w[8 * kk + 3]);
.Lsb_pfd:
	v_max_f32_e64 v44, -v44, -v44
	v_max_f32_e64 v32, -v32, -v32
	v_max_f32_e64 v37, -v37, -v37
	v_max_f32_e64 v38, -v38, -v38
	v_min_f32_e32 v44, 0x42fc0000, v44
	v_max_f32_e64 v39, -v39, -v39
	v_min_f32_e32 v32, 0x42fc0000, v32
	v_min_f32_e32 v37, 0x42fc0000, v37
	v_min_f32_e32 v105, 0x42fc0000, v38
	v_exp_f32_e32 v44, v44
	v_min_f32_e32 v39, 0x42fc0000, v39
	v_exp_f32_e32 v32, v32
	v_exp_f32_e32 v38, v37
	v_exp_f32_e32 v37, v105
	v_exp_f32_e32 v39, v39
	v_max_f32_e64 v45, -v45, -v45
	v_max_f32_e64 v33, -v33, -v33
	v_min_f32_e32 v45, 0x42fc0000, v45
	v_max_f32_e64 v34, -v34, -v34
	v_max_f32_e64 v40, -v40, -v40
	v_min_f32_e32 v33, 0x42fc0000, v33
	v_exp_f32_e32 v122, v45
	v_add_f32_e32 v45, 1.0, v44
	v_min_f32_e32 v103, 0x42fc0000, v34
	v_min_f32_e32 v109, 0x42fc0000, v40
	v_exp_f32_e32 v34, v33
	v_add_f32_e32 v40, 1.0, v32
	v_add_f32_e32 v115, 1.0, v38
	v_add_f32_e32 v116, 1.0, v37
	v_max_f32_e64 v41, -v41, -v41
	v_max_f32_e64 v42, -v42, -v42
	v_rcp_f32_e32 v124, v45
	v_max_f32_e64 v45, -v46, -v46
	v_add_f32_e32 v117, 1.0, v39
	v_rcp_f32_e32 v110, v40
	v_rcp_f32_e32 v40, v115
	v_rcp_f32_e32 v115, v116
	v_exp_f32_e32 v116, v109
	v_min_f32_e32 v41, 0x42fc0000, v41
	v_min_f32_e32 v42, 0x42fc0000, v42
	v_min_f32_e32 v45, 0x42fc0000, v45
	v_max_f32_e64 v46, -v47, -v47
	v_exp_f32_e32 v118, v41
	v_rcp_f32_e32 v41, v117
	v_exp_f32_e32 v117, v42
	v_max_f32_e64 v42, -v43, -v43
	v_exp_f32_e32 v45, v45
	v_min_f32_e32 v46, 0x42fc0000, v46
	v_min_f32_e32 v42, 0x42fc0000, v42
	v_exp_f32_e32 v123, v46
	v_max_f32_e64 v36, -v36, -v36
	v_exp_f32_e32 v33, v103
	v_add_f32_e32 v103, 1.0, v34
	v_exp_f32_e32 v119, v42
	v_min_f32_e32 v36, 0x42fc0000, v36
	v_rcp_f32_e32 v112, v103
	v_add_f32_e32 v103, 1.0, v116
	v_max_f32_e64 v35, -v35, -v35
	v_exp_f32_e32 v36, v36
	v_rcp_f32_e32 v120, v103
	v_add_f32_e32 v103, 1.0, v118
	v_add_f32_e32 v47, 1.0, v45
	v_min_f32_e32 v35, 0x42fc0000, v35
	v_rcp_f32_e32 v42, v103
	v_add_f32_e32 v43, 1.0, v117
	v_add_f32_e32 v103, 1.0, v122
	v_rcp_f32_e32 v125, v47
	v_add_f32_e32 v47, 1.0, v123
	v_exp_f32_e32 v35, v35
	v_rcp_f32_e32 v121, v43
	v_add_f32_e32 v43, 1.0, v119
	v_rcp_f32_e32 v46, v103
	v_rcp_f32_e32 v47, v47
	v_rcp_f32_e32 v43, v43
	v_add_f32_e32 v114, 1.0, v36
	v_rcp_f32_e32 v114, v114
	v_add_f32_e32 v105, 1.0, v33
	v_add_f32_e32 v113, 1.0, v35
	v_pk_mul_f32 v[44:45], v[44:45], v[124:125]
	v_pk_mul_f32 v[122:123], v[122:123], v[46:47]
	v_rcp_f32_e32 v111, v105
	v_rcp_f32_e32 v113, v113
	v_pk_mul_f32 v[116:117], v[116:117], v[120:121]
	v_pk_mul_f32 v[118:119], v[118:119], v[42:43]
	v_pk_mul_f32 v[138:139], v[44:45], v[122:123]
	v_pk_mul_f32 v[134:135], v[116:117], v[118:119]
	v_pk_mul_f32 v[138:139], v[138:139], v[138:139] op_sel:[0,1] op_sel_hi:[1,0]
	v_pk_mul_f32 v[36:37], v[36:37], v[114:115]
	v_pk_mul_f32 v[38:39], v[38:39], v[40:41]
	v_pk_mul_f32 v[134:135], v[134:135], v[134:135] op_sel:[0,1] op_sel_hi:[1,0]
	v_mov_b32_e32 v137, v138
	v_pk_mul_f32 v[130:131], v[36:37], v[38:39]
	v_mov_b32_e32 v136, v134
	v_permlane32_swap_b32_e32 v138, v137
	v_pk_mul_f32 v[32:33], v[32:33], v[110:111]
	v_pk_mul_f32 v[34:35], v[34:35], v[112:113]
	v_pk_mul_f32 v[130:131], v[130:131], v[130:131] op_sel:[0,1] op_sel_hi:[1,0]
	v_permlane32_swap_b32_e32 v134, v136
	v_mov_b32_e32 v135, v138
	v_pk_mul_f32 v[126:127], v[32:33], v[34:35]
	v_mov_b32_e32 v132, v130
	v_pk_mul_f32 v[134:135], v[134:135], v[136:137]
	v_pk_mul_f32 v[126:127], v[126:127], v[126:127] op_sel:[0,1] op_sel_hi:[1,0]
	v_permlane32_swap_b32_e32 v130, v132
	v_mov_b32_e32 v131, v134
	v_mov_b32_e32 v133, v135
	v_mov_b32_e32 v128, v126
	v_pk_mul_f32 v[130:131], v[130:131], v[132:133]
	s_nop 0
	v_permlane32_swap_b32_e32 v126, v128
	v_mov_b32_e32 v127, v130
	v_mov_b32_e32 v129, v131
	v_pk_mul_f32 v[126:127], v[126:127], v[128:129]
	v_cndmask_b32_e64 v32, 1.0, v128, s[0:1]
	v_mul_f32_e32 v105, v101, v127
	v_mul_f32_e32 v32, v32, v105
	v_mul_f32_e32 v105, v113, v32
	v_mul_f32_e32 v32, v35, v32
	v_mul_f32_e32 v35, v111, v32
	v_mul_f32_e32 v32, v33, v32
	v_cndmask_b32_e64 v36, 1.0, v132, s[0:1]
	v_mul_f32_e32 v33, v112, v32
	v_mul_f32_e32 v32, v34, v32
	v_mul_f32_e32 v34, v101, v131
	v_mul_f32_e32 v34, v36, v34
	v_mul_f32_e32 v36, v41, v34
	v_mul_f32_e32 v34, v39, v34
	v_mul_f32_e32 v39, v115, v34
	v_mul_f32_e32 v34, v37, v34
	v_cndmask_b32_e64 v44, 1.0, v136, s[0:1]
	v_mul_f32_e32 v37, v40, v34
	v_mul_f32_e32 v34, v38, v34
	v_mul_f32_e32 v38, v101, v135
	v_cndmask_b32_e64 v103, 1.0, v137, s[0:1]
	v_mul_f32_e32 v38, v44, v38
	v_mul_f32_e32 v40, v43, v38
	v_mul_f32_e32 v43, v101, v103
	v_mul_f32_e32 v38, v119, v38
	v_mul_f32_e32 v44, v47, v43
	v_mul_f32_e32 v43, v123, v43
	v_mul_f32_e32 v41, v121, v38
	v_mul_f32_e32 v38, v117, v38
	v_mul_f32_e32 v47, v125, v43
	v_mul_f32_e32 v43, v45, v43
	v_mul_f32_e32 v42, v42, v38
	v_mul_f32_e32 v38, v118, v38
	v_mul_f32_e32 v45, v46, v43
	v_mul_f32_e32 v43, v122, v43
	v_mul_f32_e32 v32, v110, v32
	v_mul_f32_e32 v34, v114, v34
	v_mul_f32_e32 v38, v120, v38
	v_mul_f32_e32 v43, v124, v43
	v_cvt_pk_bf16_f32 v32, v32, v33
	v_cvt_pk_bf16_f32 v33, v35, v105
	v_cvt_pk_bf16_f32 v34, v34, v37
	v_cvt_pk_bf16_f32 v35, v39, v36
	v_cvt_pk_bf16_f32 v36, v38, v42
	v_cvt_pk_bf16_f32 v37, v41, v40
	v_cvt_pk_bf16_f32 v38, v43, v45
	v_cvt_pk_bf16_f32 v39, v47, v44
	ds_read_b64_tr_b16 v[40:41], v108 offset:4608
	ds_read_b64_tr_b16 v[42:43], v108 offset:5760
	ds_read_b64_tr_b16 v[46:47], v108 offset:5824
	ds_read_b64_tr_b16 v[44:45], v108 offset:4672
	s_waitcnt lgkmcnt(2)
	v_mfma_f32_32x32x16_bf16 v[16:31], v[40:43], v[32:35], v[16:31]
	s_waitcnt lgkmcnt(0)
	v_mfma_f32_32x32x16_bf16 v[0:15], v[44:47], v[32:35], v[0:15]
	ds_read_b64_tr_b16 v[32:33], v108 offset:6912
	ds_read_b64_tr_b16 v[34:35], v108 offset:8064
	ds_read_b64_tr_b16 v[42:43], v108 offset:8128
	ds_read_b64_tr_b16 v[40:41], v108 offset:6976
	s_waitcnt lgkmcnt(2)
	v_mfma_f32_32x32x16_bf16 v[16:31], v[32:35], v[36:39], v[16:31]
	v_mul_f32_e32 v32, v126, v127
	v_mul_f32_e32 v101, v101, v32
	v_cmp_gt_f32_e32 vcc, s3, v101
	s_cmp_lg_u64 vcc, exec
	s_cselect_b64 s[50:51], -1, 0
	s_cmp_gt_u32 s48, 63
	s_cselect_b64 s[66:67], -1, 0
	s_waitcnt lgkmcnt(0)
	v_mfma_f32_32x32x16_bf16 v[0:15], v[40:43], v[36:39], v[0:15]
	s_and_b64 s[50:51], s[66:67], s[50:51]
	s_sub_i32 s48, s48, 32
	s_and_b64 vcc, exec, s[50:51]
	s_cbranch_vccz .LBB0_271
.LBB0_276:
	s_cmp_eq_u32 s48, 32
	s_waitcnt vmcnt(7)
	ds_write_b128 v106, v[64:67]
	s_waitcnt vmcnt(6)
	ds_write_b128 v106, v[68:71] offset:1152
	s_waitcnt vmcnt(5)
	ds_write_b128 v106, v[72:75] offset:2304
	s_waitcnt vmcnt(4)
	ds_write_b128 v106, v[76:79] offset:3456
	ds_read_b128 v[118:121], v107
	ds_read_b128 v[110:113], v107 offset:32
	ds_read_b128 v[122:125], v107 offset:64
	ds_read_b128 v[114:117], v107 offset:96
	s_waitcnt vmcnt(3)
	ds_write_b128 v106, v[80:83] offset:4608
	s_waitcnt vmcnt(2)
	ds_write_b128 v106, v[84:87] offset:5760
	s_waitcnt vmcnt(1)
	ds_write_b128 v106, v[88:91] offset:6912
	s_waitcnt vmcnt(0)
	ds_write_b128 v106, v[92:95] offset:8064
	s_branch .LBB0_275
